# memory K/V epilogue: V^T written through an LDS transpose with 16-byte stores; row sums of squares loaded once
# baseline (speedup 1.0000x reference)
.LBB0_1088:
	s_and_b64 vcc, exec, s[50:51]
	s_cbranch_vccz .LBB0_1085
	v_and_b32_e32 v180, 63, v214
	v_lshrrev_b32_e32 v181, 6, v214
	v_lshlrev_b32_e32 v181, 10, v181
	v_add_u32_e32 v181, 0x20000, v181
	v_lshl_add_u32 v177, v180, 4, v181
	v_and_b32_e32 v182, 15, v180
	v_lshrrev_b32_e32 v183, 4, v180
	v_lshlrev_b32_e32 v176, 8, v183
	v_lshl_add_u32 v176, v182, 1, v176
	v_add_u32_e32 v176, v176, v181
	v_lshrrev_b32_e32 v178, 1, v180
	v_lshlrev_b32_e32 v178, 9, v178
	v_and_b32_e32 v179, 1, v180
	v_lshl_add_u32 v178, v179, 4, v178
	v_lshlrev_b32_e32 v179, 12, v183
	v_sub_u32_e32 v178, v178, v179
	v_lshlrev_b32_e32 v179, 1, v182
	v_sub_u32_e32 v178, v178, v179
	v_ashrrev_i32_e32 v179, 31, v178
	s_waitcnt lgkmcnt(0)
	v_lshl_add_u64 v[128:129], v[144:145], 2, s[90:91]
	global_load_dword v130, v[128:129], off
	global_load_dword v168, v[128:129], off offset:64
	global_load_dword v169, v[128:129], off offset:128
	global_load_dword v170, v[128:129], off offset:192
	global_load_dword v171, v[128:129], off offset:512
	global_load_dword v188, v[128:129], off offset:576
	global_load_dword v189, v[128:129], off offset:640
	global_load_dword v190, v[128:129], off offset:704
	s_lshl_b32 s0, s66, 3
	v_add_u32_e32 v131, s4, v174
	s_add_i32 s16, s81, s0
	s_movk_i32 s0, 0x3ff
	v_cmp_lt_i32_e32 vcc, s0, v131
	s_movk_i32 s0, 0x400
	v_cmp_gt_i32_e64 s[0:1], s0, v131
	s_ashr_i32 s67, s66, 31
	v_mov_b32_e32 v129, v193
	v_cndmask_b32_e64 v128, v238, v239, s[0:1]
	s_lshl_b64 s[20:21], s[66:67], 23
	v_lshl_add_u64 v[128:129], s[86:87], 0, v[128:129]
	v_lshlrev_b64 v[146:147], 12, v[144:145]
	v_and_b32_e32 v132, 0x3ff, v131
	v_lshlrev_b32_e32 v131, 8, v131
	s_ashr_i32 s17, s16, 31
	v_lshl_add_u64 v[142:143], v[128:129], 0, s[20:21]
	v_mov_b32_e32 v139, v193
	v_lshlrev_b32_e32 v138, 2, v132
	v_and_b32_e32 v131, 0x30000, v131
	s_lshl_b64 s[30:31], s[16:17], 18
	v_lshl_add_u64 v[128:129], v[142:143], 0, v[146:147]
	v_or_b32_e32 v150, s30, v131
	v_mov_b32_e32 v151, s31
	v_lshl_add_u64 v[140:141], v[128:129], 0, v[138:139]
	v_ashrrev_i32_e32 v173, 31, v172
	v_lshlrev_b32_sdwa v136, v240, v174 dst_sel:DWORD dst_unused:UNUSED_PAD src0_sel:DWORD src1_sel:BYTE_0
	s_waitcnt vmcnt(0) lgkmcnt(0)
	v_fmamk_f32 v130, v130, 0x3a800000, v215
	v_rsq_f32_e32 v148, v130
	s_nop 0
	v_pk_mul_f32 v[134:135], v[126:127], v[148:149] op_sel_hi:[1,0]
	v_pk_mul_f32 v[132:133], v[124:125], v[148:149] op_sel_hi:[1,0]
	v_pk_mul_f32 v[130:131], v[122:123], v[148:149] op_sel_hi:[1,0]
	v_pk_mul_f32 v[128:129], v[120:121], v[148:149] op_sel_hi:[1,0]
	global_store_dwordx4 v[140:141], v[132:135], off
	global_store_dwordx4 v[140:141], v[128:131], off offset:16
	v_lshl_add_u64 v[140:141], v[150:151], 1, s[96:97]
	s_and_saveexec_b64 s[0:1], vcc
	s_xor_b64 s[0:1], exec, s[0:1]
	s_cbranch_execz .LBB0_1091
	v_mov_b32_e32 v137, v193
	v_lshl_add_u64 v[144:145], v[140:141], 0, v[136:137]
	v_lshl_add_u64 v[144:145], v[172:173], 1, v[144:145]
	v_cvt_pk_bf16_f32 v180, v132, s0
	ds_write_b16 v176, v180
	v_cvt_pk_bf16_f32 v180, v133, s0
	ds_write_b16 v176, v180 offset:32
	v_cvt_pk_bf16_f32 v180, v134, s0
	ds_write_b16 v176, v180 offset:64
	v_cvt_pk_bf16_f32 v180, v135, s0
	ds_write_b16 v176, v180 offset:96
	v_cvt_pk_bf16_f32 v180, v128, s0
	ds_write_b16 v176, v180 offset:128
	v_cvt_pk_bf16_f32 v180, v129, s0
	ds_write_b16 v176, v180 offset:160
	v_cvt_pk_bf16_f32 v180, v130, s0
	ds_write_b16 v176, v180 offset:192
	v_cvt_pk_bf16_f32 v180, v131, s0
	ds_write_b16 v176, v180 offset:224
	s_waitcnt lgkmcnt(0)
	ds_read_b128 v[184:187], v177
	v_lshl_add_u64 v[182:183], v[144:145], 0, v[178:179]
	s_waitcnt lgkmcnt(0)
	global_store_dwordx4 v[182:183], v[184:187], off

.LBB0_1093:
	s_or_b64 exec, exec, s[0:1]
	v_add_u32_e32 v137, 0x80, v174
	v_add_u32_e32 v139, s4, v137
	s_movk_i32 s4, 0x400
	v_mov_b32_e32 v149, v148
	v_mov_b32_e32 v132, v148
	v_mov_b32_e32 v133, v148
	v_cmp_gt_i32_e64 s[4:5], s4, v139
	v_pk_mul_f32 v[130:131], v[94:95], v[132:133]
	v_pk_mul_f32 v[128:129], v[92:93], v[148:149]
	v_pk_mul_f32 v[134:135], v[90:91], v[132:133]
	v_pk_mul_f32 v[132:133], v[88:89], v[148:149]
	v_cndmask_b32_e64 v148, v238, v239, s[4:5]
	v_mov_b32_e32 v149, v193
	s_movk_i32 s0, 0x3ff
	v_lshl_add_u64 v[148:149], s[86:87], 0, v[148:149]
	v_cmp_lt_i32_e64 s[0:1], s0, v139
	v_lshl_add_u64 v[152:153], v[148:149], 0, s[20:21]
	v_and_b32_e32 v145, 0x3ff, v139
	v_lshlrev_b32_e32 v139, 8, v139
	v_lshl_add_u64 v[146:147], v[152:153], 0, v[146:147]
	v_lshlrev_b32_e32 v154, 2, v145
	v_mov_b32_e32 v155, v193
	v_and_b32_e32 v139, 0x30000, v139
	v_lshl_add_u64 v[146:147], v[146:147], 0, v[154:155]
	v_or_b32_e32 v158, s30, v139
	v_mov_b32_e32 v159, s31
	global_store_dwordx4 v[146:147], v[128:131], off
	global_store_dwordx4 v[146:147], v[132:135], off offset:16
	v_lshlrev_b32_sdwa v146, v240, v137 dst_sel:DWORD dst_unused:UNUSED_PAD src0_sel:DWORD src1_sel:BYTE_0
	v_lshl_add_u64 v[148:149], v[158:159], 1, s[96:97]
	s_and_saveexec_b64 s[4:5], s[0:1]
	s_xor_b64 s[4:5], exec, s[4:5]
	s_cbranch_execz .LBB0_1095
	v_mov_b32_e32 v147, v193
	v_lshl_add_u64 v[156:157], v[148:149], 0, v[146:147]
	v_lshl_add_u64 v[156:157], v[172:173], 1, v[156:157]
	v_cvt_pk_bf16_f32 v180, v128, s0
	ds_write_b16 v176, v180
	v_cvt_pk_bf16_f32 v180, v129, s0
	ds_write_b16 v176, v180 offset:32
	v_cvt_pk_bf16_f32 v180, v130, s0
	ds_write_b16 v176, v180 offset:64
	v_cvt_pk_bf16_f32 v180, v131, s0
	ds_write_b16 v176, v180 offset:96
	v_cvt_pk_bf16_f32 v180, v132, s0
	ds_write_b16 v176, v180 offset:128
	v_cvt_pk_bf16_f32 v180, v133, s0
	ds_write_b16 v176, v180 offset:160
	v_cvt_pk_bf16_f32 v180, v134, s0
	ds_write_b16 v176, v180 offset:192
	v_cvt_pk_bf16_f32 v180, v135, s0
	ds_write_b16 v176, v180 offset:224
	s_waitcnt lgkmcnt(0)
	ds_read_b128 v[184:187], v177
	v_lshl_add_u64 v[182:183], v[156:157], 0, v[178:179]
	s_waitcnt lgkmcnt(0)
	global_store_dwordx4 v[182:183], v[184:187], off

.LBB0_1097:
	s_or_b64 exec, exec, s[4:5]
	v_add_u32_e32 v164, 16, v172
	v_add_u32_e32 v128, s63, v164
	v_ashrrev_i32_e32 v129, 31, v128
	v_lshl_add_u64 v[130:131], v[128:129], 2, s[90:91]
	v_mov_b32_e32 v130, v168
	v_lshlrev_b64 v[160:161], 12, v[128:129]
	v_mov_b32_e32 v139, v193
	v_lshl_add_u64 v[128:129], v[142:143], 0, v[160:161]
	v_lshl_add_u64 v[166:167], v[128:129], 0, v[138:139]
	s_waitcnt lgkmcnt(0)
	v_fmamk_f32 v130, v130, 0x3a800000, v215
	v_rsq_f32_e32 v162, v130
	s_nop 0
	v_pk_mul_f32 v[134:135], v[118:119], v[162:163] op_sel_hi:[1,0]
	v_pk_mul_f32 v[132:133], v[116:117], v[162:163] op_sel_hi:[1,0]
	v_pk_mul_f32 v[130:131], v[114:115], v[162:163] op_sel_hi:[1,0]
	v_pk_mul_f32 v[128:129], v[112:113], v[162:163] op_sel_hi:[1,0]
	global_store_dwordx4 v[166:167], v[132:135], off
	global_store_dwordx4 v[166:167], v[128:131], off offset:16
	s_and_saveexec_b64 s[4:5], vcc
	s_xor_b64 s[4:5], exec, s[4:5]
	s_cbranch_execz .LBB0_1099
	v_mov_b32_e32 v137, v193
	v_lshl_add_u64 v[166:167], v[140:141], 0, v[136:137]
	v_lshl_add_u64 v[166:167], v[172:173], 1, v[166:167]
	v_cvt_pk_bf16_f32 v180, v132, s0
	ds_write_b16 v176, v180
	v_cvt_pk_bf16_f32 v180, v133, s0
	ds_write_b16 v176, v180 offset:32
	v_cvt_pk_bf16_f32 v180, v134, s0
	ds_write_b16 v176, v180 offset:64
	v_cvt_pk_bf16_f32 v180, v135, s0
	ds_write_b16 v176, v180 offset:96
	v_cvt_pk_bf16_f32 v180, v128, s0
	ds_write_b16 v176, v180 offset:128
	v_cvt_pk_bf16_f32 v180, v129, s0
	ds_write_b16 v176, v180 offset:160
	v_cvt_pk_bf16_f32 v180, v130, s0
	ds_write_b16 v176, v180 offset:192
	v_cvt_pk_bf16_f32 v180, v131, s0
	ds_write_b16 v176, v180 offset:224
	s_waitcnt lgkmcnt(0)
	ds_read_b128 v[184:187], v177
	v_lshl_add_u64 v[182:183], v[166:167], 0, v[178:179]
	s_waitcnt lgkmcnt(0)
	global_store_dwordx4 v[182:183], v[184:187], off offset:32

.LBB0_1101:
	s_or_b64 exec, exec, s[4:5]
	v_mov_b32_e32 v163, v162
	v_mov_b32_e32 v132, v162
	v_mov_b32_e32 v133, v162
	v_lshl_add_u64 v[160:161], v[152:153], 0, v[160:161]
	v_mov_b32_e32 v155, v193
	v_pk_mul_f32 v[130:131], v[86:87], v[132:133]
	v_pk_mul_f32 v[128:129], v[84:85], v[162:163]
	v_pk_mul_f32 v[134:135], v[82:83], v[132:133]
	v_pk_mul_f32 v[132:133], v[80:81], v[162:163]
	v_lshl_add_u64 v[160:161], v[160:161], 0, v[154:155]
	global_store_dwordx4 v[160:161], v[128:131], off
	global_store_dwordx4 v[160:161], v[132:135], off offset:16
	s_and_saveexec_b64 s[4:5], s[0:1]
	s_xor_b64 s[4:5], exec, s[4:5]
	s_cbranch_execz .LBB0_1103
	v_mov_b32_e32 v147, v193
	v_lshl_add_u64 v[160:161], v[148:149], 0, v[146:147]
	v_lshl_add_u64 v[160:161], v[172:173], 1, v[160:161]
	v_cvt_pk_bf16_f32 v180, v128, s0
	ds_write_b16 v176, v180
	v_cvt_pk_bf16_f32 v180, v129, s0
	ds_write_b16 v176, v180 offset:32
	v_cvt_pk_bf16_f32 v180, v130, s0
	ds_write_b16 v176, v180 offset:64
	v_cvt_pk_bf16_f32 v180, v131, s0
	ds_write_b16 v176, v180 offset:96
	v_cvt_pk_bf16_f32 v180, v132, s0
	ds_write_b16 v176, v180 offset:128
	v_cvt_pk_bf16_f32 v180, v133, s0
	ds_write_b16 v176, v180 offset:160
	v_cvt_pk_bf16_f32 v180, v134, s0
	ds_write_b16 v176, v180 offset:192
	v_cvt_pk_bf16_f32 v180, v135, s0
	ds_write_b16 v176, v180 offset:224
	s_waitcnt lgkmcnt(0)
	ds_read_b128 v[184:187], v177
	v_lshl_add_u64 v[182:183], v[160:161], 0, v[178:179]
	s_waitcnt lgkmcnt(0)
	global_store_dwordx4 v[182:183], v[184:187], off offset:32

.LBB0_1105:
	s_or_b64 exec, exec, s[4:5]
	v_add_u32_e32 v164, 32, v172
	v_add_u32_e32 v128, s63, v164
	v_ashrrev_i32_e32 v129, 31, v128
	v_lshl_add_u64 v[130:131], v[128:129], 2, s[90:91]
	v_mov_b32_e32 v130, v169
	v_lshlrev_b64 v[160:161], 12, v[128:129]
	v_mov_b32_e32 v139, v193
	v_lshl_add_u64 v[128:129], v[142:143], 0, v[160:161]
	v_lshl_add_u64 v[166:167], v[128:129], 0, v[138:139]
	s_waitcnt lgkmcnt(0)
	v_fmamk_f32 v130, v130, 0x3a800000, v215
	v_rsq_f32_e32 v162, v130
	s_nop 0
	v_pk_mul_f32 v[134:135], v[110:111], v[162:163] op_sel_hi:[1,0]
	v_pk_mul_f32 v[132:133], v[108:109], v[162:163] op_sel_hi:[1,0]
	v_pk_mul_f32 v[130:131], v[106:107], v[162:163] op_sel_hi:[1,0]
	v_pk_mul_f32 v[128:129], v[104:105], v[162:163] op_sel_hi:[1,0]
	global_store_dwordx4 v[166:167], v[132:135], off
	global_store_dwordx4 v[166:167], v[128:131], off offset:16
	s_and_saveexec_b64 s[4:5], vcc
	s_xor_b64 s[4:5], exec, s[4:5]
	s_cbranch_execz .LBB0_1107
	v_mov_b32_e32 v137, v193
	v_lshl_add_u64 v[166:167], v[140:141], 0, v[136:137]
	v_lshl_add_u64 v[166:167], v[172:173], 1, v[166:167]
	v_cvt_pk_bf16_f32 v180, v132, s0
	ds_write_b16 v176, v180
	v_cvt_pk_bf16_f32 v180, v133, s0
	ds_write_b16 v176, v180 offset:32
	v_cvt_pk_bf16_f32 v180, v134, s0
	ds_write_b16 v176, v180 offset:64
	v_cvt_pk_bf16_f32 v180, v135, s0
	ds_write_b16 v176, v180 offset:96
	v_cvt_pk_bf16_f32 v180, v128, s0
	ds_write_b16 v176, v180 offset:128
	v_cvt_pk_bf16_f32 v180, v129, s0
	ds_write_b16 v176, v180 offset:160
	v_cvt_pk_bf16_f32 v180, v130, s0
	ds_write_b16 v176, v180 offset:192
	v_cvt_pk_bf16_f32 v180, v131, s0
	ds_write_b16 v176, v180 offset:224
	s_waitcnt lgkmcnt(0)
	ds_read_b128 v[184:187], v177
	v_lshl_add_u64 v[182:183], v[166:167], 0, v[178:179]
	s_waitcnt lgkmcnt(0)
	global_store_dwordx4 v[182:183], v[184:187], off offset:64

.LBB0_1109:
	s_or_b64 exec, exec, s[4:5]
	v_mov_b32_e32 v163, v162
	v_mov_b32_e32 v132, v162
	v_mov_b32_e32 v133, v162
	v_lshl_add_u64 v[160:161], v[152:153], 0, v[160:161]
	v_mov_b32_e32 v155, v193
	v_pk_mul_f32 v[130:131], v[78:79], v[132:133]
	v_pk_mul_f32 v[128:129], v[76:77], v[162:163]
	v_pk_mul_f32 v[134:135], v[74:75], v[132:133]
	v_pk_mul_f32 v[132:133], v[72:73], v[162:163]
	v_lshl_add_u64 v[160:161], v[160:161], 0, v[154:155]
	global_store_dwordx4 v[160:161], v[128:131], off
	global_store_dwordx4 v[160:161], v[132:135], off offset:16
	s_and_saveexec_b64 s[4:5], s[0:1]
	s_xor_b64 s[4:5], exec, s[4:5]
	s_cbranch_execz .LBB0_1111
	v_mov_b32_e32 v147, v193
	v_lshl_add_u64 v[160:161], v[148:149], 0, v[146:147]
	v_lshl_add_u64 v[160:161], v[172:173], 1, v[160:161]
	v_cvt_pk_bf16_f32 v180, v128, s0
	ds_write_b16 v176, v180
	v_cvt_pk_bf16_f32 v180, v129, s0
	ds_write_b16 v176, v180 offset:32
	v_cvt_pk_bf16_f32 v180, v130, s0
	ds_write_b16 v176, v180 offset:64
	v_cvt_pk_bf16_f32 v180, v131, s0
	ds_write_b16 v176, v180 offset:96
	v_cvt_pk_bf16_f32 v180, v132, s0
	ds_write_b16 v176, v180 offset:128
	v_cvt_pk_bf16_f32 v180, v133, s0
	ds_write_b16 v176, v180 offset:160
	v_cvt_pk_bf16_f32 v180, v134, s0
	ds_write_b16 v176, v180 offset:192
	v_cvt_pk_bf16_f32 v180, v135, s0
	ds_write_b16 v176, v180 offset:224
	s_waitcnt lgkmcnt(0)
	ds_read_b128 v[184:187], v177
	v_lshl_add_u64 v[182:183], v[160:161], 0, v[178:179]
	s_waitcnt lgkmcnt(0)
	global_store_dwordx4 v[182:183], v[184:187], off offset:64

.LBB0_1113:
	s_or_b64 exec, exec, s[4:5]
	v_add_u32_e32 v164, 48, v172
	v_add_u32_e32 v128, s63, v164
	v_ashrrev_i32_e32 v129, 31, v128
	v_lshl_add_u64 v[130:131], v[128:129], 2, s[90:91]
	v_mov_b32_e32 v130, v170
	v_lshlrev_b64 v[160:161], 12, v[128:129]
	v_mov_b32_e32 v139, v193
	v_lshl_add_u64 v[128:129], v[142:143], 0, v[160:161]
	v_lshl_add_u64 v[166:167], v[128:129], 0, v[138:139]
	s_waitcnt lgkmcnt(0)
	v_fmamk_f32 v130, v130, 0x3a800000, v215
	v_rsq_f32_e32 v162, v130
	s_nop 0
	v_pk_mul_f32 v[134:135], v[102:103], v[162:163] op_sel_hi:[1,0]
	v_pk_mul_f32 v[132:133], v[100:101], v[162:163] op_sel_hi:[1,0]
	v_pk_mul_f32 v[130:131], v[98:99], v[162:163] op_sel_hi:[1,0]
	v_pk_mul_f32 v[128:129], v[96:97], v[162:163] op_sel_hi:[1,0]
	global_store_dwordx4 v[166:167], v[132:135], off
	global_store_dwordx4 v[166:167], v[128:131], off offset:16
	s_and_saveexec_b64 s[4:5], vcc
	s_xor_b64 s[4:5], exec, s[4:5]
	s_cbranch_execz .LBB0_1115
	v_mov_b32_e32 v137, v193
	v_lshl_add_u64 v[166:167], v[140:141], 0, v[136:137]
	v_lshl_add_u64 v[166:167], v[172:173], 1, v[166:167]
	v_cvt_pk_bf16_f32 v180, v132, s0
	ds_write_b16 v176, v180
	v_cvt_pk_bf16_f32 v180, v133, s0
	ds_write_b16 v176, v180 offset:32
	v_cvt_pk_bf16_f32 v180, v134, s0
	ds_write_b16 v176, v180 offset:64
	v_cvt_pk_bf16_f32 v180, v135, s0
	ds_write_b16 v176, v180 offset:96
	v_cvt_pk_bf16_f32 v180, v128, s0
	ds_write_b16 v176, v180 offset:128
	v_cvt_pk_bf16_f32 v180, v129, s0
	ds_write_b16 v176, v180 offset:160
	v_cvt_pk_bf16_f32 v180, v130, s0
	ds_write_b16 v176, v180 offset:192
	v_cvt_pk_bf16_f32 v180, v131, s0
	ds_write_b16 v176, v180 offset:224
	s_waitcnt lgkmcnt(0)
	ds_read_b128 v[184:187], v177
	v_lshl_add_u64 v[182:183], v[166:167], 0, v[178:179]
	s_waitcnt lgkmcnt(0)
	global_store_dwordx4 v[182:183], v[184:187], off offset:96

.LBB0_1117:
	s_or_b64 exec, exec, s[4:5]
	v_mov_b32_e32 v163, v162
	v_mov_b32_e32 v132, v162
	v_mov_b32_e32 v133, v162
	v_lshl_add_u64 v[160:161], v[152:153], 0, v[160:161]
	v_mov_b32_e32 v155, v193
	v_pk_mul_f32 v[130:131], v[70:71], v[132:133]
	v_pk_mul_f32 v[128:129], v[68:69], v[162:163]
	v_pk_mul_f32 v[134:135], v[66:67], v[132:133]
	v_pk_mul_f32 v[132:133], v[64:65], v[162:163]
	v_lshl_add_u64 v[160:161], v[160:161], 0, v[154:155]
	global_store_dwordx4 v[160:161], v[128:131], off
	global_store_dwordx4 v[160:161], v[132:135], off offset:16
	s_and_saveexec_b64 s[4:5], s[0:1]
	s_xor_b64 s[4:5], exec, s[4:5]
	s_cbranch_execz .LBB0_1119
	v_mov_b32_e32 v147, v193
	v_lshl_add_u64 v[160:161], v[148:149], 0, v[146:147]
	v_lshl_add_u64 v[160:161], v[172:173], 1, v[160:161]
	v_cvt_pk_bf16_f32 v180, v128, s0
	ds_write_b16 v176, v180
	v_cvt_pk_bf16_f32 v180, v129, s0
	ds_write_b16 v176, v180 offset:32
	v_cvt_pk_bf16_f32 v180, v130, s0
	ds_write_b16 v176, v180 offset:64
	v_cvt_pk_bf16_f32 v180, v131, s0
	ds_write_b16 v176, v180 offset:96
	v_cvt_pk_bf16_f32 v180, v132, s0
	ds_write_b16 v176, v180 offset:128
	v_cvt_pk_bf16_f32 v180, v133, s0
	ds_write_b16 v176, v180 offset:160
	v_cvt_pk_bf16_f32 v180, v134, s0
	ds_write_b16 v176, v180 offset:192
	v_cvt_pk_bf16_f32 v180, v135, s0
	ds_write_b16 v176, v180 offset:224
	s_waitcnt lgkmcnt(0)
	ds_read_b128 v[184:187], v177
	v_lshl_add_u64 v[182:183], v[160:161], 0, v[178:179]
	s_waitcnt lgkmcnt(0)
	global_store_dwordx4 v[182:183], v[184:187], off offset:96

.LBB0_1121:
	s_or_b64 exec, exec, s[4:5]
	v_add_u32_e32 v164, 0x80, v172
	v_add_u32_e32 v128, s63, v164
	v_ashrrev_i32_e32 v129, 31, v128
	v_lshl_add_u64 v[130:131], v[128:129], 2, s[90:91]
	v_mov_b32_e32 v130, v171
	v_lshlrev_b64 v[160:161], 12, v[128:129]
	v_mov_b32_e32 v139, v193
	v_lshl_add_u64 v[128:129], v[142:143], 0, v[160:161]
	v_lshl_add_u64 v[166:167], v[128:129], 0, v[138:139]
	s_waitcnt lgkmcnt(0)
	v_fmamk_f32 v130, v130, 0x3a800000, v215
	v_rsq_f32_e32 v162, v130
	s_nop 0
	v_pk_mul_f32 v[134:135], v[62:63], v[162:163] op_sel_hi:[1,0]
	v_pk_mul_f32 v[132:133], v[60:61], v[162:163] op_sel_hi:[1,0]
	v_pk_mul_f32 v[130:131], v[58:59], v[162:163] op_sel_hi:[1,0]
	v_pk_mul_f32 v[128:129], v[56:57], v[162:163] op_sel_hi:[1,0]
	global_store_dwordx4 v[166:167], v[132:135], off
	global_store_dwordx4 v[166:167], v[128:131], off offset:16
	s_and_saveexec_b64 s[4:5], vcc
	s_xor_b64 s[4:5], exec, s[4:5]
	s_cbranch_execz .LBB0_1123
	v_mov_b32_e32 v137, v193
	v_lshl_add_u64 v[166:167], v[140:141], 0, v[136:137]
	v_lshl_add_u64 v[166:167], v[172:173], 1, v[166:167]
	v_cvt_pk_bf16_f32 v180, v132, s0
	ds_write_b16 v176, v180
	v_cvt_pk_bf16_f32 v180, v133, s0
	ds_write_b16 v176, v180 offset:32
	v_cvt_pk_bf16_f32 v180, v134, s0
	ds_write_b16 v176, v180 offset:64
	v_cvt_pk_bf16_f32 v180, v135, s0
	ds_write_b16 v176, v180 offset:96
	v_cvt_pk_bf16_f32 v180, v128, s0
	ds_write_b16 v176, v180 offset:128
	v_cvt_pk_bf16_f32 v180, v129, s0
	ds_write_b16 v176, v180 offset:160
	v_cvt_pk_bf16_f32 v180, v130, s0
	ds_write_b16 v176, v180 offset:192
	v_cvt_pk_bf16_f32 v180, v131, s0
	ds_write_b16 v176, v180 offset:224
	s_waitcnt lgkmcnt(0)
	ds_read_b128 v[184:187], v177
	v_lshl_add_u64 v[182:183], v[166:167], 0, v[178:179]
	s_waitcnt lgkmcnt(0)
	global_store_dwordx4 v[182:183], v[184:187], off offset:256

.LBB0_1125:
	s_or_b64 exec, exec, s[4:5]
	v_mov_b32_e32 v163, v162
	v_mov_b32_e32 v132, v162
	v_mov_b32_e32 v133, v162
	v_lshl_add_u64 v[160:161], v[152:153], 0, v[160:161]
	v_mov_b32_e32 v155, v193
	v_pk_mul_f32 v[130:131], v[30:31], v[132:133]
	v_pk_mul_f32 v[128:129], v[28:29], v[162:163]
	v_pk_mul_f32 v[134:135], v[26:27], v[132:133]
	v_pk_mul_f32 v[132:133], v[24:25], v[162:163]
	v_lshl_add_u64 v[160:161], v[160:161], 0, v[154:155]
	global_store_dwordx4 v[160:161], v[128:131], off
	global_store_dwordx4 v[160:161], v[132:135], off offset:16
	s_and_saveexec_b64 s[4:5], s[0:1]
	s_xor_b64 s[4:5], exec, s[4:5]
	s_cbranch_execz .LBB0_1127
	v_mov_b32_e32 v147, v193
	v_lshl_add_u64 v[160:161], v[148:149], 0, v[146:147]
	v_lshl_add_u64 v[160:161], v[172:173], 1, v[160:161]
	v_cvt_pk_bf16_f32 v180, v128, s0
	ds_write_b16 v176, v180
	v_cvt_pk_bf16_f32 v180, v129, s0
	ds_write_b16 v176, v180 offset:32
	v_cvt_pk_bf16_f32 v180, v130, s0
	ds_write_b16 v176, v180 offset:64
	v_cvt_pk_bf16_f32 v180, v131, s0
	ds_write_b16 v176, v180 offset:96
	v_cvt_pk_bf16_f32 v180, v132, s0
	ds_write_b16 v176, v180 offset:128
	v_cvt_pk_bf16_f32 v180, v133, s0
	ds_write_b16 v176, v180 offset:160
	v_cvt_pk_bf16_f32 v180, v134, s0
	ds_write_b16 v176, v180 offset:192
	v_cvt_pk_bf16_f32 v180, v135, s0
	ds_write_b16 v176, v180 offset:224
	s_waitcnt lgkmcnt(0)
	ds_read_b128 v[184:187], v177
	v_lshl_add_u64 v[182:183], v[160:161], 0, v[178:179]
	s_waitcnt lgkmcnt(0)
	global_store_dwordx4 v[182:183], v[184:187], off offset:256

.LBB0_1129:
	s_or_b64 exec, exec, s[4:5]
	v_add_u32_e32 v164, 0x90, v172
	v_add_u32_e32 v128, s63, v164
	v_ashrrev_i32_e32 v129, 31, v128
	v_lshl_add_u64 v[130:131], v[128:129], 2, s[90:91]
	v_mov_b32_e32 v130, v188
	v_lshlrev_b64 v[160:161], 12, v[128:129]
	v_mov_b32_e32 v139, v193
	v_lshl_add_u64 v[128:129], v[142:143], 0, v[160:161]
	v_lshl_add_u64 v[166:167], v[128:129], 0, v[138:139]
	s_waitcnt lgkmcnt(0)
	v_fmamk_f32 v130, v130, 0x3a800000, v215
	v_rsq_f32_e32 v162, v130
	s_nop 0
	v_pk_mul_f32 v[134:135], v[54:55], v[162:163] op_sel_hi:[1,0]
	v_pk_mul_f32 v[132:133], v[52:53], v[162:163] op_sel_hi:[1,0]
	v_pk_mul_f32 v[130:131], v[50:51], v[162:163] op_sel_hi:[1,0]
	v_pk_mul_f32 v[128:129], v[48:49], v[162:163] op_sel_hi:[1,0]
	global_store_dwordx4 v[166:167], v[132:135], off
	global_store_dwordx4 v[166:167], v[128:131], off offset:16
	s_and_saveexec_b64 s[4:5], vcc
	s_xor_b64 s[4:5], exec, s[4:5]
	s_cbranch_execz .LBB0_1131
	v_mov_b32_e32 v137, v193
	v_lshl_add_u64 v[166:167], v[140:141], 0, v[136:137]
	v_lshl_add_u64 v[166:167], v[172:173], 1, v[166:167]
	v_cvt_pk_bf16_f32 v180, v132, s0
	ds_write_b16 v176, v180
	v_cvt_pk_bf16_f32 v180, v133, s0
	ds_write_b16 v176, v180 offset:32
	v_cvt_pk_bf16_f32 v180, v134, s0
	ds_write_b16 v176, v180 offset:64
	v_cvt_pk_bf16_f32 v180, v135, s0
	ds_write_b16 v176, v180 offset:96
	v_cvt_pk_bf16_f32 v180, v128, s0
	ds_write_b16 v176, v180 offset:128
	v_cvt_pk_bf16_f32 v180, v129, s0
	ds_write_b16 v176, v180 offset:160
	v_cvt_pk_bf16_f32 v180, v130, s0
	ds_write_b16 v176, v180 offset:192
	v_cvt_pk_bf16_f32 v180, v131, s0
	ds_write_b16 v176, v180 offset:224
	s_waitcnt lgkmcnt(0)
	ds_read_b128 v[184:187], v177
	v_lshl_add_u64 v[182:183], v[166:167], 0, v[178:179]
	s_waitcnt lgkmcnt(0)
	global_store_dwordx4 v[182:183], v[184:187], off offset:288

.LBB0_1133:
	s_or_b64 exec, exec, s[4:5]
	v_mov_b32_e32 v163, v162
	v_mov_b32_e32 v132, v162
	v_mov_b32_e32 v133, v162
	v_lshl_add_u64 v[160:161], v[152:153], 0, v[160:161]
	v_mov_b32_e32 v155, v193
	v_pk_mul_f32 v[130:131], v[22:23], v[132:133]
	v_pk_mul_f32 v[128:129], v[20:21], v[162:163]
	v_pk_mul_f32 v[134:135], v[18:19], v[132:133]
	v_pk_mul_f32 v[132:133], v[16:17], v[162:163]
	v_lshl_add_u64 v[160:161], v[160:161], 0, v[154:155]
	global_store_dwordx4 v[160:161], v[128:131], off
	global_store_dwordx4 v[160:161], v[132:135], off offset:16
	s_and_saveexec_b64 s[4:5], s[0:1]
	s_xor_b64 s[4:5], exec, s[4:5]
	s_cbranch_execz .LBB0_1135
	v_mov_b32_e32 v147, v193
	v_lshl_add_u64 v[160:161], v[148:149], 0, v[146:147]
	v_lshl_add_u64 v[160:161], v[172:173], 1, v[160:161]
	v_cvt_pk_bf16_f32 v180, v128, s0
	ds_write_b16 v176, v180
	v_cvt_pk_bf16_f32 v180, v129, s0
	ds_write_b16 v176, v180 offset:32
	v_cvt_pk_bf16_f32 v180, v130, s0
	ds_write_b16 v176, v180 offset:64
	v_cvt_pk_bf16_f32 v180, v131, s0
	ds_write_b16 v176, v180 offset:96
	v_cvt_pk_bf16_f32 v180, v132, s0
	ds_write_b16 v176, v180 offset:128
	v_cvt_pk_bf16_f32 v180, v133, s0
	ds_write_b16 v176, v180 offset:160
	v_cvt_pk_bf16_f32 v180, v134, s0
	ds_write_b16 v176, v180 offset:192
	v_cvt_pk_bf16_f32 v180, v135, s0
	ds_write_b16 v176, v180 offset:224
	s_waitcnt lgkmcnt(0)
	ds_read_b128 v[184:187], v177
	v_lshl_add_u64 v[182:183], v[160:161], 0, v[178:179]
	s_waitcnt lgkmcnt(0)
	global_store_dwordx4 v[182:183], v[184:187], off offset:288

.LBB0_1137:
	s_or_b64 exec, exec, s[4:5]
	v_add_u32_e32 v164, 0xa0, v172
	v_add_u32_e32 v128, s63, v164
	v_ashrrev_i32_e32 v129, 31, v128
	v_lshl_add_u64 v[130:131], v[128:129], 2, s[90:91]
	v_mov_b32_e32 v130, v189
	v_lshlrev_b64 v[160:161], 12, v[128:129]
	v_mov_b32_e32 v139, v193
	v_lshl_add_u64 v[128:129], v[142:143], 0, v[160:161]
	v_lshl_add_u64 v[166:167], v[128:129], 0, v[138:139]
	s_waitcnt lgkmcnt(0)
	v_fmamk_f32 v130, v130, 0x3a800000, v215
	v_rsq_f32_e32 v162, v130
	s_nop 0
	v_pk_mul_f32 v[134:135], v[46:47], v[162:163] op_sel_hi:[1,0]
	v_pk_mul_f32 v[132:133], v[44:45], v[162:163] op_sel_hi:[1,0]
	v_pk_mul_f32 v[130:131], v[42:43], v[162:163] op_sel_hi:[1,0]
	v_pk_mul_f32 v[128:129], v[40:41], v[162:163] op_sel_hi:[1,0]
	global_store_dwordx4 v[166:167], v[132:135], off
	global_store_dwordx4 v[166:167], v[128:131], off offset:16
	s_and_saveexec_b64 s[4:5], vcc
	s_xor_b64 s[4:5], exec, s[4:5]
	s_cbranch_execz .LBB0_1139
	v_mov_b32_e32 v137, v193
	v_lshl_add_u64 v[166:167], v[140:141], 0, v[136:137]
	v_lshl_add_u64 v[166:167], v[172:173], 1, v[166:167]
	v_cvt_pk_bf16_f32 v180, v132, s0
	ds_write_b16 v176, v180
	v_cvt_pk_bf16_f32 v180, v133, s0
	ds_write_b16 v176, v180 offset:32
	v_cvt_pk_bf16_f32 v180, v134, s0
	ds_write_b16 v176, v180 offset:64
	v_cvt_pk_bf16_f32 v180, v135, s0
	ds_write_b16 v176, v180 offset:96
	v_cvt_pk_bf16_f32 v180, v128, s0
	ds_write_b16 v176, v180 offset:128
	v_cvt_pk_bf16_f32 v180, v129, s0
	ds_write_b16 v176, v180 offset:160
	v_cvt_pk_bf16_f32 v180, v130, s0
	ds_write_b16 v176, v180 offset:192
	v_cvt_pk_bf16_f32 v180, v131, s0
	ds_write_b16 v176, v180 offset:224
	s_waitcnt lgkmcnt(0)
	ds_read_b128 v[184:187], v177
	v_lshl_add_u64 v[182:183], v[166:167], 0, v[178:179]
	s_waitcnt lgkmcnt(0)
	global_store_dwordx4 v[182:183], v[184:187], off offset:320

.LBB0_1141:
	s_or_b64 exec, exec, s[4:5]
	v_mov_b32_e32 v163, v162
	v_mov_b32_e32 v132, v162
	v_mov_b32_e32 v133, v162
	v_lshl_add_u64 v[160:161], v[152:153], 0, v[160:161]
	v_mov_b32_e32 v155, v193
	v_pk_mul_f32 v[130:131], v[14:15], v[132:133]
	v_pk_mul_f32 v[128:129], v[12:13], v[162:163]
	v_pk_mul_f32 v[134:135], v[10:11], v[132:133]
	v_pk_mul_f32 v[132:133], v[8:9], v[162:163]
	v_lshl_add_u64 v[160:161], v[160:161], 0, v[154:155]
	global_store_dwordx4 v[160:161], v[128:131], off
	global_store_dwordx4 v[160:161], v[132:135], off offset:16
	s_and_saveexec_b64 s[4:5], s[0:1]
	s_xor_b64 s[4:5], exec, s[4:5]
	s_cbranch_execz .LBB0_1143
	v_mov_b32_e32 v147, v193
	v_lshl_add_u64 v[160:161], v[148:149], 0, v[146:147]
	v_lshl_add_u64 v[160:161], v[172:173], 1, v[160:161]
	v_cvt_pk_bf16_f32 v180, v128, s0
	ds_write_b16 v176, v180
	v_cvt_pk_bf16_f32 v180, v129, s0
	ds_write_b16 v176, v180 offset:32
	v_cvt_pk_bf16_f32 v180, v130, s0
	ds_write_b16 v176, v180 offset:64
	v_cvt_pk_bf16_f32 v180, v131, s0
	ds_write_b16 v176, v180 offset:96
	v_cvt_pk_bf16_f32 v180, v132, s0
	ds_write_b16 v176, v180 offset:128
	v_cvt_pk_bf16_f32 v180, v133, s0
	ds_write_b16 v176, v180 offset:160
	v_cvt_pk_bf16_f32 v180, v134, s0
	ds_write_b16 v176, v180 offset:192
	v_cvt_pk_bf16_f32 v180, v135, s0
	ds_write_b16 v176, v180 offset:224
	s_waitcnt lgkmcnt(0)
	ds_read_b128 v[184:187], v177
	v_lshl_add_u64 v[182:183], v[160:161], 0, v[178:179]
	s_waitcnt lgkmcnt(0)
	global_store_dwordx4 v[182:183], v[184:187], off offset:320

.LBB0_1145:
	s_or_b64 exec, exec, s[4:5]
	v_add_u32_e32 v164, 0xb0, v172
	v_add_u32_e32 v128, s63, v164
	v_ashrrev_i32_e32 v129, 31, v128
	v_lshl_add_u64 v[130:131], v[128:129], 2, s[90:91]
	v_mov_b32_e32 v130, v190
	v_lshlrev_b64 v[160:161], 12, v[128:129]
	v_mov_b32_e32 v139, v193
	v_lshl_add_u64 v[128:129], v[142:143], 0, v[160:161]
	v_lshl_add_u64 v[138:139], v[128:129], 0, v[138:139]
	s_waitcnt lgkmcnt(0)
	v_fmamk_f32 v130, v130, 0x3a800000, v215
	v_rsq_f32_e32 v162, v130
	s_nop 0
	v_pk_mul_f32 v[134:135], v[38:39], v[162:163] op_sel_hi:[1,0]
	v_pk_mul_f32 v[132:133], v[36:37], v[162:163] op_sel_hi:[1,0]
	v_pk_mul_f32 v[130:131], v[34:35], v[162:163] op_sel_hi:[1,0]
	v_pk_mul_f32 v[128:129], v[32:33], v[162:163] op_sel_hi:[1,0]
	global_store_dwordx4 v[138:139], v[132:135], off
	global_store_dwordx4 v[138:139], v[128:131], off offset:16
	s_and_saveexec_b64 s[4:5], vcc
	s_xor_b64 s[4:5], exec, s[4:5]
	s_cbranch_execz .LBB0_1147
	v_mov_b32_e32 v137, v193
	v_lshl_add_u64 v[136:137], v[140:141], 0, v[136:137]
	v_lshl_add_u64 v[136:137], v[172:173], 1, v[136:137]
	v_cvt_pk_bf16_f32 v180, v132, s0
	ds_write_b16 v176, v180
	v_cvt_pk_bf16_f32 v180, v133, s0
	ds_write_b16 v176, v180 offset:32
	v_cvt_pk_bf16_f32 v180, v134, s0
	ds_write_b16 v176, v180 offset:64
	v_cvt_pk_bf16_f32 v180, v135, s0
	ds_write_b16 v176, v180 offset:96
	v_cvt_pk_bf16_f32 v180, v128, s0
	ds_write_b16 v176, v180 offset:128
	v_cvt_pk_bf16_f32 v180, v129, s0
	ds_write_b16 v176, v180 offset:160
	v_cvt_pk_bf16_f32 v180, v130, s0
	ds_write_b16 v176, v180 offset:192
	v_cvt_pk_bf16_f32 v180, v131, s0
	ds_write_b16 v176, v180 offset:224
	s_waitcnt lgkmcnt(0)
	ds_read_b128 v[184:187], v177
	v_lshl_add_u64 v[182:183], v[136:137], 0, v[178:179]
	s_waitcnt lgkmcnt(0)
	global_store_dwordx4 v[182:183], v[184:187], off offset:352

.LBB0_1149:
	s_or_b64 exec, exec, s[4:5]
	v_mov_b32_e32 v163, v162
	v_mov_b32_e32 v132, v162
	v_mov_b32_e32 v133, v162
	v_lshl_add_u64 v[138:139], v[152:153], 0, v[160:161]
	v_mov_b32_e32 v155, v193
	v_pk_mul_f32 v[130:131], v[6:7], v[132:133]
	v_pk_mul_f32 v[128:129], v[4:5], v[162:163]
	v_pk_mul_f32 v[134:135], v[2:3], v[132:133]
	v_pk_mul_f32 v[132:133], v[0:1], v[162:163]
	v_lshl_add_u64 v[138:139], v[138:139], 0, v[154:155]
	global_store_dwordx4 v[138:139], v[128:131], off
	global_store_dwordx4 v[138:139], v[132:135], off offset:16
	s_and_saveexec_b64 s[4:5], s[0:1]
	s_xor_b64 s[0:1], exec, s[4:5]
	s_cbranch_execz .LBB0_1151
	v_mov_b32_e32 v147, v193
	v_lshl_add_u64 v[136:137], v[148:149], 0, v[146:147]
	v_lshl_add_u64 v[136:137], v[172:173], 1, v[136:137]
	v_cvt_pk_bf16_f32 v180, v128, s0
	ds_write_b16 v176, v180
	v_cvt_pk_bf16_f32 v180, v129, s0
	ds_write_b16 v176, v180 offset:32
	v_cvt_pk_bf16_f32 v180, v130, s0
	ds_write_b16 v176, v180 offset:64
	v_cvt_pk_bf16_f32 v180, v131, s0
	ds_write_b16 v176, v180 offset:96
	v_cvt_pk_bf16_f32 v180, v132, s0
	ds_write_b16 v176, v180 offset:128
	v_cvt_pk_bf16_f32 v180, v133, s0
	ds_write_b16 v176, v180 offset:160
	v_cvt_pk_bf16_f32 v180, v134, s0
	ds_write_b16 v176, v180 offset:192
	v_cvt_pk_bf16_f32 v180, v135, s0
	ds_write_b16 v176, v180 offset:224
	s_waitcnt lgkmcnt(0)
	ds_read_b128 v[184:187], v177
	v_lshl_add_u64 v[182:183], v[136:137], 0, v[178:179]
	s_waitcnt lgkmcnt(0)
	global_store_dwordx4 v[182:183], v[184:187], off offset:352
